# XCD-local barriers at B4 B5 B9 (no top-level sync, no L2 writeback), sample-row ordering by cross-XCD unit counters
# speedup vs baseline: 1.0092x; 1.0034x over previous
; __device__ __forceinline__ unsigned xb_add(unsigned* p, unsigned v) { return __hip_atomic_fetch_add(p, v, __ATOMIC_RELAXED, __HIP_MEMORY_SCOPE_AGENT); }
; __device__ __forceinline__ void xcd_barrier(const XcdBarrier& b) {
;     asm volatile("s_waitcnt vmcnt(0)" ::: "memory");
;     __syncthreads();
;     if (threadIdx.x == 0) {
;         unsigned* bar = b.bar;
;         __builtin_amdgcn_s_waitcnt(0);
;         unsigned nloc = b.st[0], nx = b.st[1];
;         if (nloc == 0u) { xcd_barrier_complete(bar, b.x, nloc, nx); b.st[0] = nloc; b.st[1] = nx; }
;         const unsigned old = xb_add(&bar[XB_XSUB(b.x)], 1u);
;         const unsigned gen = old / nloc;
;         if (old + 1u == (gen + 1u) * nloc) {
.LBB0_766:
	s_mov_b64 s[6:7], exec
	v_readlane_b32 s3, v254, 19
	s_lshl_b32 s3, s3, 8
	v_mbcnt_lo_u32_b32 v1, s6, 0
	s_add_u32 s4, s58, s3
	v_mbcnt_hi_u32_b32 v1, s7, v1
	s_addc_u32 s5, s59, 0
	v_cmp_eq_u32_e32 vcc, 0, v1
	s_and_saveexec_b64 s[10:11], vcc
	s_cbranch_execz .LBB0_768
	s_bcnt1_i32_b64 s3, s[6:7]
	v_mov_b32_e32 v3, 0x1000
	v_mov_b32_e32 v4, s3
	global_atomic_add v3, v3, v4, s[4:5] offset:1024 sc0
	s_cmp_lt_u32 s2, 32
	s_cbranch_scc0 .Lcnt_skip_4
	v_mov_b32_e32 v5, 0x3a00
	global_atomic_add v5, v4, s[58:59]
.Lcnt_skip_4:
.LBB0_768:
	s_or_b64 exec, exec, s[10:11]
	v_cvt_f32_u32_e32 v4, v2
	s_waitcnt vmcnt(0)
	v_readfirstlane_b32 s3, v3
	v_sub_u32_e32 v3, 0, v2
	v_rcp_iflag_f32_e32 v4, v4
	v_add_u32_e32 v5, s3, v1
	v_mul_f32_e32 v4, 0x4f7ffffe, v4
	v_cvt_u32_f32_e32 v4, v4
	v_mul_lo_u32 v1, v3, v4
	v_mul_hi_u32 v1, v4, v1
	v_add_u32_e32 v1, v4, v1
	v_mul_hi_u32 v1, v5, v1
	v_mul_lo_u32 v3, v1, v2
	v_sub_u32_e32 v3, v5, v3
	v_add_u32_e32 v4, 1, v1
	v_cmp_ge_u32_e32 vcc, v3, v2
	s_nop 1
	v_cndmask_b32_e32 v1, v1, v4, vcc
	v_sub_u32_e32 v4, v3, v2
	v_cndmask_b32_e32 v3, v3, v4, vcc
	v_add_u32_e32 v4, 1, v1
	v_cmp_ge_u32_e32 vcc, v3, v2
	v_add_u32_e32 v3, 1, v5
	s_nop 0
	v_cndmask_b32_e32 v1, v1, v4, vcc
	v_mul_lo_u32 v4, v2, v1
	v_add_u32_e32 v2, v4, v2
	v_cmp_ne_u32_e32 vcc, v3, v2
	s_and_saveexec_b64 s[6:7], vcc
	s_xor_b64 s[6:7], exec, s[6:7]
	s_cbranch_execz .LBB0_782
	s_waitcnt lgkmcnt(0)
	v_mov_b32_e32 v0, 0x2000
	global_load_dword v0, v0, s[4:5] offset:1024 sc1
	s_add_u32 s12, s4, 0x2400
	s_addc_u32 s13, s5, 0
	s_waitcnt vmcnt(0)
	v_cmp_eq_u32_e32 vcc, v0, v1
	s_and_saveexec_b64 s[10:11], vcc
	s_cbranch_execz .LBB0_781
	s_mov_b32 s3, 1
	s_mov_b64 s[14:15], 0
	v_mov_b32_e32 v0, 0
	s_branch .LBB0_772

; __device__ __forceinline__ unsigned xb_add(unsigned* p, unsigned v) { return __hip_atomic_fetch_add(p, v, __ATOMIC_RELAXED, __HIP_MEMORY_SCOPE_AGENT); }
; __device__ __forceinline__ void xcd_barrier(const XcdBarrier& b) {
;     ...
;         const unsigned old = xb_add(&bar[XB_XSUB(b.x)], 1u);
;         const unsigned gen = old / nloc;
;         if (old + 1u == (gen + 1u) * nloc) {
;             __builtin_amdgcn_fence(__ATOMIC_RELEASE, "agent");
;             asm volatile("s_waitcnt vmcnt(0)" ::: "memory");
;             const unsigned og = xb_add(&bar[XB_TOP], 1u);
;             const unsigned tg = og / nx;
;             if (og + 1u == (tg + 1u) * nx) xb_add(&bar[XB_TOPGEN], 1u);
.LBB0_782:
	s_andn2_saveexec_b64 s[6:7], s[6:7]
	s_cbranch_execz .LBB0_802
	s_mov_b64 s[6:7], exec
	v_readlane_b32 s3, v255, 40
	s_waitcnt lgkmcnt(0)
	s_cmp_eq_u32 s3, 0
	s_cbranch_scc1 .Lxloc_4
	buffer_wbl2 sc1
	s_waitcnt lgkmcnt(0)
	s_waitcnt vmcnt(0)
	v_mbcnt_lo_u32_b32 v1, s6, 0
	v_mbcnt_hi_u32_b32 v1, s7, v1
	v_cmp_eq_u32_e32 vcc, 0, v1
	s_and_saveexec_b64 s[10:11], vcc
	s_cbranch_execz .LBB0_785
	s_bcnt1_i32_b64 s3, s[6:7]
	v_mov_b32_e32 v2, 0x3000
	v_mov_b32_e32 v3, s3
	global_atomic_add v2, v2, v3, s[58:59] offset:1024 sc0

; __device__ __forceinline__ unsigned xb_ld(unsigned* p)              { return __hip_atomic_load(p, __ATOMIC_RELAXED, __HIP_MEMORY_SCOPE_AGENT); }
; __device__ __forceinline__ unsigned xb_add(unsigned* p, unsigned v) { return __hip_atomic_fetch_add(p, v, __ATOMIC_RELAXED, __HIP_MEMORY_SCOPE_AGENT); }
; #define XB_SPIN(cond, bar) do { unsigned _sp = 0; while (cond) { __builtin_amdgcn_s_sleep(1); \
;     if ((++_sp & 255u) == 0u) { if (xb_ld(&(bar)[XB_TMO])) break; if (_sp > XB_SPIN_CAP) { atomicAdd(&(bar)[XB_TMO], 1u); break; } } } } while (0)
; __device__ __forceinline__ void xcd_barrier(const XcdBarrier& b) {
;     ...
;             else XB_SPIN(xb_ld(&bar[XB_TOPGEN]) == tg, bar);
;             __builtin_amdgcn_fence(__ATOMIC_ACQUIRE, "agent");
;             xb_add(&bar[XB_XGEN(b.x)], 1u);
;             asm volatile("s_waitcnt vmcnt(0)" ::: "memory");
.Lxloc_4:
	s_mov_b64 s[6:7], exec
	v_mbcnt_lo_u32_b32 v0, s6, 0
	v_mbcnt_hi_u32_b32 v0, s7, v0
	v_cmp_eq_u32_e32 vcc, 0, v0
	s_waitcnt vmcnt(0)
	buffer_inv sc1
	s_and_saveexec_b64 s[10:11], vcc
	s_cbranch_execz .LBB0_801
	s_bcnt1_i32_b64 s3, s[6:7]
	v_mov_b32_e32 v0, 0x2000
	v_mov_b32_e32 v1, s3
	global_atomic_add v0, v1, s[4:5] offset:1024

; template <class Epi, bool PAIR>
; __device__ __forceinline__ void small_gemm(LAS unsigned char* lds, const bf16_t* A, int lda, const bf16_t* B, int ldb, int K, int nrg, int nct, size_t row_base, int col_base, const Epi& E, int G, int c) {
;     ...
;     for (int unit = c; unit < nrg * nct; unit += G) {
;         const int rg = unit % nrg, ct = unit / nrg;
;         f32x4 acc[4][4];
; #pragma unroll
;         for (int mi = 0; mi < 4; ++mi)
; #pragma unroll
;             for (int ni = 0; ni < 4; ++ni) acc[mi][ni] = (f32x4){0.f, 0.f, 0.f, 0.f};
;         const bf16_t* ap = A + (size_t)(rg * 64 + fr) * lda + k0 + fq * 8;
;         const bf16_t* bp;
;         if (PAIR) { const int ch0 = 32 * ct; bp = B + (size_t)(DSSM + 256 * (ch0 >> 7) + (ch0 & 127) + fr) * ldb + k0 + fq * 8; }
;         else bp = B + (size_t)(ct * 64 + fr) * ldb + k0 + fq * 8;
.LBB0_844:
	v_mov_b32_e32 v4, v202
	s_cmp_lt_i32 s2, 64
	s_cselect_b64 s[8:9], -1, 0
	v_readfirstlane_b32 s0, v4
	s_cmp_gt_i32 s2, 63
	v_and_b32_e32 v203, 7, v202
	s_cbranch_scc1 .LBB0_849
	v_mov_b32_e32 v0, 0x3a00
	s_mov_b32 s4, 0x40000
.Lsmp_p5:
	global_load_dword v1, v0, s[58:59] sc0 sc1
	s_waitcnt vmcnt(0)
	v_readfirstlane_b32 s5, v1
	s_cmpk_ge_u32 s5, 32
	s_cbranch_scc1 .Lsmg_p5
	s_sleep 1
	s_sub_u32 s4, s4, 1
	s_cmp_lg_u32 s4, 0
	s_cbranch_scc1 .Lsmp_p5
.Lsmg_p5:
	buffer_inv sc1
	s_lshl_b32 s1, s0, 1
	s_and_b32 s4, s1, 0xffffff80
	s_ashr_i32 s5, s4, 31
	s_lshl_b64 s[4:5], s[4:5], 1
	s_add_u32 s6, s58, s4
	s_addc_u32 s7, s59, s5
	v_and_b32_e32 v6, 48, v4
	v_mov_b32_e32 v7, 0
	v_lshl_add_u64 v[0:1], s[6:7], 0, v[6:7]
	s_mov_b64 s[6:7], 0x1a100000
	v_lshl_add_u64 v[0:1], v[0:1], 0, s[6:7]
	v_readlane_b32 s6, v254, 57
	v_readlane_b32 s7, v254, 58
	s_add_u32 s4, s6, s4
	v_and_b32_e32 v10, 15, v4
	s_addc_u32 s5, s7, s5
	s_and_b32 s0, s0, 0xfffffc0
	s_waitcnt lgkmcnt(0)
	v_lshl_add_u64 v[2:3], s[4:5], 0, v[6:7]
	v_or_b32_e32 v5, s0, v10
	v_ashrrev_i32_e32 v7, 3, v4
	v_and_b32_e32 v4, 7, v4
	s_movk_i32 s0, 0x110
	v_add_u32_e32 v6, 0, v6
	v_lshlrev_b32_e32 v8, 5, v4
	v_lshlrev_b32_e32 v12, 3, v4
	v_mul_lo_u32 v4, v5, s0
	v_add_u32_e32 v22, v6, v4
	v_mbcnt_lo_u32_b32 v4, -1, 0
	v_mul_lo_u32 v5, v7, s0
	v_mbcnt_hi_u32_b32 v23, -1, v4
	v_add3_u32 v13, 0, v8, v5
	v_and_b32_e32 v4, 64, v23
	s_mov_b32 s3, 0x8000
	v_add_u32_e32 v11, 0x8000, v7
	v_cmp_eq_u32_e32 vcc, 0, v203
	v_add_u32_e32 v14, 0x11000, v13
	v_add_u32_e32 v15, 0x11010, v13
	v_add_u32_e32 v16, 0x15400, v13
	v_add_u32_e32 v17, 0x15410, v13
	v_add_u32_e32 v18, 0x19800, v13
	v_add_u32_e32 v19, 0x19810, v13
	v_add_u32_e32 v20, 0x1dc00, v13
	v_add_u32_e32 v21, 0x1dc10, v13
	s_lshl_b32 s4, s2, 6
	s_mov_b32 s5, 0x10000
	s_mov_b32 s7, 0x18000
	s_mov_b32 s6, 0x3f9837f0
	v_xor_b32_e32 v24, 1, v23
	v_add_u32_e32 v25, 64, v4
	v_xor_b32_e32 v26, 2, v23
	v_xor_b32_e32 v27, 4, v23
	s_mov_b32 s16, s2
	s_branch .LBB0_847

; __device__ __forceinline__ unsigned xb_add(unsigned* p, unsigned v) { return __hip_atomic_fetch_add(p, v, __ATOMIC_RELAXED, __HIP_MEMORY_SCOPE_AGENT); }
; __device__ __forceinline__ void xcd_barrier(const XcdBarrier& b) {
;     asm volatile("s_waitcnt vmcnt(0)" ::: "memory");
;     __syncthreads();
;     if (threadIdx.x == 0) {
;         unsigned* bar = b.bar;
;         __builtin_amdgcn_s_waitcnt(0);
;         unsigned nloc = b.st[0], nx = b.st[1];
;         if (nloc == 0u) { xcd_barrier_complete(bar, b.x, nloc, nx); b.st[0] = nloc; b.st[1] = nx; }
;         const unsigned old = xb_add(&bar[XB_XSUB(b.x)], 1u);
;         const unsigned gen = old / nloc;
;         if (old + 1u == (gen + 1u) * nloc) {
.LBB0_865:
	s_mov_b64 s[10:11], exec
	v_readlane_b32 s3, v254, 19
	s_lshl_b32 s3, s3, 8
	v_mbcnt_lo_u32_b32 v1, s10, 0
	s_add_u32 s6, s58, s3
	v_mbcnt_hi_u32_b32 v1, s11, v1
	s_addc_u32 s7, s59, 0
	v_cmp_eq_u32_e32 vcc, 0, v1
	s_and_saveexec_b64 s[16:17], vcc
	s_cbranch_execz .LBB0_867
	s_bcnt1_i32_b64 s3, s[10:11]
	v_mov_b32_e32 v3, 0x1000
	v_mov_b32_e32 v4, s3
	global_atomic_add v3, v3, v4, s[6:7] offset:1024 sc0
	s_cmp_lt_u32 s2, 64
	s_cbranch_scc0 .Lcnt_skip_5
	v_mov_b32_e32 v5, 0x3a80
	global_atomic_add v5, v4, s[58:59]
.Lcnt_skip_5:
.LBB0_867:
	s_or_b64 exec, exec, s[16:17]
	v_cvt_f32_u32_e32 v4, v2
	s_waitcnt vmcnt(0)
	v_readfirstlane_b32 s3, v3
	v_sub_u32_e32 v3, 0, v2
	v_rcp_iflag_f32_e32 v4, v4
	v_add_u32_e32 v5, s3, v1
	v_mul_f32_e32 v4, 0x4f7ffffe, v4
	v_cvt_u32_f32_e32 v4, v4
	v_mul_lo_u32 v1, v3, v4
	v_mul_hi_u32 v1, v4, v1
	v_add_u32_e32 v1, v4, v1
	v_mul_hi_u32 v1, v5, v1
	v_mul_lo_u32 v3, v1, v2
	v_sub_u32_e32 v3, v5, v3
	v_add_u32_e32 v4, 1, v1
	v_cmp_ge_u32_e32 vcc, v3, v2
	s_nop 1
	v_cndmask_b32_e32 v1, v1, v4, vcc
	v_sub_u32_e32 v4, v3, v2
	v_cndmask_b32_e32 v3, v3, v4, vcc
	v_add_u32_e32 v4, 1, v1
	v_cmp_ge_u32_e32 vcc, v3, v2
	v_add_u32_e32 v3, 1, v5
	s_nop 0
	v_cndmask_b32_e32 v1, v1, v4, vcc
	v_mul_lo_u32 v4, v2, v1
	v_add_u32_e32 v2, v4, v2
	v_cmp_ne_u32_e32 vcc, v3, v2
	s_and_saveexec_b64 s[4:5], vcc
	s_xor_b64 s[10:11], exec, s[4:5]
	s_cbranch_execz .LBB0_881
	s_waitcnt lgkmcnt(0)
	v_mov_b32_e32 v0, 0x2000
	global_load_dword v0, v0, s[6:7] offset:1024 sc1
	s_add_u32 s18, s6, 0x2400
	s_addc_u32 s19, s7, 0
	s_waitcnt vmcnt(0)
	v_cmp_eq_u32_e32 vcc, v0, v1
	s_and_saveexec_b64 s[16:17], vcc
	s_cbranch_execz .LBB0_880
	s_mov_b32 s3, 1
	s_mov_b64 s[20:21], 0
	v_mov_b32_e32 v0, 0
	s_branch .LBB0_871

; __device__ __forceinline__ unsigned xb_add(unsigned* p, unsigned v) { return __hip_atomic_fetch_add(p, v, __ATOMIC_RELAXED, __HIP_MEMORY_SCOPE_AGENT); }
; __device__ __forceinline__ void xcd_barrier(const XcdBarrier& b) {
;     ...
;         const unsigned old = xb_add(&bar[XB_XSUB(b.x)], 1u);
;         const unsigned gen = old / nloc;
;         if (old + 1u == (gen + 1u) * nloc) {
;             __builtin_amdgcn_fence(__ATOMIC_RELEASE, "agent");
;             asm volatile("s_waitcnt vmcnt(0)" ::: "memory");
;             const unsigned og = xb_add(&bar[XB_TOP], 1u);
;             const unsigned tg = og / nx;
;             if (og + 1u == (tg + 1u) * nx) xb_add(&bar[XB_TOPGEN], 1u);
.LBB0_881:
	s_andn2_saveexec_b64 s[4:5], s[10:11]
	s_cbranch_execz .LBB0_901
	s_mov_b64 s[10:11], exec
	v_readlane_b32 s3, v255, 40
	s_waitcnt lgkmcnt(0)
	s_cmp_eq_u32 s3, 0
	s_cbranch_scc1 .Lxloc_5
	buffer_wbl2 sc1
	s_waitcnt lgkmcnt(0)
	s_waitcnt vmcnt(0)
	v_mbcnt_lo_u32_b32 v1, s10, 0
	v_mbcnt_hi_u32_b32 v1, s11, v1
	v_cmp_eq_u32_e32 vcc, 0, v1
	s_and_saveexec_b64 s[16:17], vcc
	s_cbranch_execz .LBB0_884
	s_bcnt1_i32_b64 s3, s[10:11]
	v_mov_b32_e32 v2, 0x3000
	v_mov_b32_e32 v3, s3
	global_atomic_add v2, v2, v3, s[58:59] offset:1024 sc0

; __device__ __forceinline__ unsigned xb_ld(unsigned* p)              { return __hip_atomic_load(p, __ATOMIC_RELAXED, __HIP_MEMORY_SCOPE_AGENT); }
; __device__ __forceinline__ unsigned xb_add(unsigned* p, unsigned v) { return __hip_atomic_fetch_add(p, v, __ATOMIC_RELAXED, __HIP_MEMORY_SCOPE_AGENT); }
; #define XB_SPIN(cond, bar) do { unsigned _sp = 0; while (cond) { __builtin_amdgcn_s_sleep(1); \
;     if ((++_sp & 255u) == 0u) { if (xb_ld(&(bar)[XB_TMO])) break; if (_sp > XB_SPIN_CAP) { atomicAdd(&(bar)[XB_TMO], 1u); break; } } } } while (0)
; __device__ __forceinline__ void xcd_barrier(const XcdBarrier& b) {
;     ...
;             else XB_SPIN(xb_ld(&bar[XB_TOPGEN]) == tg, bar);
;             __builtin_amdgcn_fence(__ATOMIC_ACQUIRE, "agent");
;             xb_add(&bar[XB_XGEN(b.x)], 1u);
;             asm volatile("s_waitcnt vmcnt(0)" ::: "memory");
.Lxloc_5:
	s_mov_b64 s[10:11], exec
	v_mbcnt_lo_u32_b32 v0, s10, 0
	v_mbcnt_hi_u32_b32 v0, s11, v0
	v_cmp_eq_u32_e32 vcc, 0, v0
	s_waitcnt vmcnt(0)
	buffer_inv sc1
	s_and_saveexec_b64 s[16:17], vcc
	s_cbranch_execz .LBB0_900
	s_bcnt1_i32_b64 s3, s[10:11]
	v_mov_b32_e32 v0, 0x2000
	v_mov_b32_e32 v1, s3
	global_atomic_add v0, v1, s[6:7] offset:1024

; template <class Epi, bool PAIR>
; __device__ __forceinline__ void small_gemm(LAS unsigned char* lds, const bf16_t* A, int lda, const bf16_t* B, int ldb, int K, int nrg, int nct, size_t row_base, int col_base, const Epi& E, int G, int c) {
;     ...
;     for (int unit = c; unit < nrg * nct; unit += G) {
;         const int rg = unit % nrg, ct = unit / nrg;
;         f32x4 acc[4][4];
; #pragma unroll
;         for (int mi = 0; mi < 4; ++mi)
; #pragma unroll
;             for (int ni = 0; ni < 4; ++ni) acc[mi][ni] = (f32x4){0.f, 0.f, 0.f, 0.f};
;         const bf16_t* ap = A + (size_t)(rg * 64 + fr) * lda + k0 + fq * 8;
;         const bf16_t* bp;
;         if (PAIR) { const int ch0 = 32 * ct; bp = B + (size_t)(DSSM + 256 * (ch0 >> 7) + (ch0 & 127) + fr) * ldb + k0 + fq * 8; }
;         else bp = B + (size_t)(ct * 64 + fr) * ldb + k0 + fq * 8;
.LBB0_949:
	v_cndmask_b32_e64 v1, 0, 1, s[8:9]
	v_cmp_ne_u32_e64 s[4:5], 1, v1
	v_mov_b32_e32 v0, v202
	s_andn2_b64 vcc, exec, s[8:9]
	v_writelane_b32 v254, s4, 61
	v_readfirstlane_b32 s3, v0
	s_nop 0
	v_writelane_b32 v254, s5, 62
	s_cbranch_vccnz .LBB0_952
	v_mov_b32_e32 v2, 0x3a80
	s_mov_b32 s4, 0x40000
.Lsmp_p6:
	global_load_dword v3, v2, s[58:59] sc0 sc1
	s_waitcnt vmcnt(0)
	v_readfirstlane_b32 s5, v3
	s_cmpk_ge_u32 s5, 64
	s_cbranch_scc1 .Lsmg_p6
	s_sleep 1
	s_sub_u32 s4, s4, 1
	s_cmp_lg_u32 s4, 0
	s_cbranch_scc1 .Lsmp_p6
.Lsmg_p6:
	buffer_inv sc1
	s_lshl_b32 s4, s3, 1
	s_and_b32 s4, s4, 0xffffff80
	s_ashr_i32 s5, s4, 31
	s_lshl_b64 s[4:5], s[4:5], 1
	s_add_u32 s6, s58, s4
	s_addc_u32 s7, s59, s5
	v_and_b32_e32 v2, 48, v0
	v_mov_b32_e32 v3, 0
	v_lshl_add_u64 v[4:5], s[6:7], 0, v[2:3]
	s_mov_b64 s[6:7], 0x7800000
	v_lshl_add_u64 v[36:37], v[4:5], 0, s[6:7]
	v_readlane_b32 s6, v254, 59
	v_readlane_b32 s7, v254, 60
	s_add_u32 s4, s6, s4
	s_addc_u32 s5, s7, s5
	v_and_b32_e32 v40, 15, v0
	v_lshl_add_u64 v[38:39], s[4:5], 0, v[2:3]
	s_and_b32 s3, s3, 0xfffffc0
	v_ashrrev_i32_e32 v3, 3, v0
	v_and_b32_e32 v0, 7, v0
	s_movk_i32 s4, 0x110
	v_or_b32_e32 v1, s3, v40
	v_lshlrev_b32_e32 v4, 5, v0
	v_lshlrev_b32_e32 v42, 3, v0
	v_mul_lo_u32 v0, v3, s4
	v_add_u32_e32 v2, 0, v2
	v_add3_u32 v43, 0, v4, v0
	v_mul_lo_u32 v0, v1, s4
	s_mov_b32 s3, 0x8000
	v_add_u32_e32 v41, 0x8000, v3
	v_add_u32_e32 v44, 0x11000, v43
	v_add_u32_e32 v45, 0x11010, v43
	v_add_u32_e32 v46, 0x15400, v43
	v_add_u32_e32 v47, 0x15410, v43
	v_add_u32_e32 v48, 0x19800, v43
	v_add_u32_e32 v49, 0x19810, v43
	v_add_u32_e32 v50, 0x1dc00, v43
	v_add_u32_e32 v51, 0x1dc10, v43
	s_lshl_b32 s4, s2, 6
	s_mov_b32 s5, 0x10000
	s_mov_b32 s6, 0x18000
	v_add_u32_e32 v52, v2, v0
	s_mov_b32 s8, 0x3a800000
	s_mov_b32 s16, 0x3d800000
	s_mov_b32 s7, s2

; __device__ __forceinline__ unsigned xb_add(unsigned* p, unsigned v) { return __hip_atomic_fetch_add(p, v, __ATOMIC_RELAXED, __HIP_MEMORY_SCOPE_AGENT); }
; __device__ __forceinline__ void xcd_barrier(const XcdBarrier& b) {
;     asm volatile("s_waitcnt vmcnt(0)" ::: "memory");
;     __syncthreads();
;     if (threadIdx.x == 0) {
;         unsigned* bar = b.bar;
;         __builtin_amdgcn_s_waitcnt(0);
;         unsigned nloc = b.st[0], nx = b.st[1];
;         if (nloc == 0u) { xcd_barrier_complete(bar, b.x, nloc, nx); b.st[0] = nloc; b.st[1] = nx; }
;         const unsigned old = xb_add(&bar[XB_XSUB(b.x)], 1u);
;         const unsigned gen = old / nloc;
;         if (old + 1u == (gen + 1u) * nloc) {
.LBB0_1404:
	s_mov_b64 s[10:11], exec
	v_readlane_b32 s3, v254, 19
	s_lshl_b32 s3, s3, 8
	v_mbcnt_lo_u32_b32 v1, s10, 0
	s_add_u32 s8, s58, s3
	v_mbcnt_hi_u32_b32 v1, s11, v1
	s_addc_u32 s9, s59, 0
	v_cmp_eq_u32_e32 vcc, 0, v1
	s_and_saveexec_b64 s[12:13], vcc
	s_cbranch_execz .LBB0_1406
	s_bcnt1_i32_b64 s3, s[10:11]
	v_mov_b32_e32 v3, 0x1000
	v_mov_b32_e32 v4, s3
	global_atomic_add v3, v3, v4, s[8:9] offset:1024 sc0
	v_mov_b32_e32 v5, 0x3b00
	global_atomic_add v5, v4, s[58:59]

; __device__ __forceinline__ unsigned xb_add(unsigned* p, unsigned v) { return __hip_atomic_fetch_add(p, v, __ATOMIC_RELAXED, __HIP_MEMORY_SCOPE_AGENT); }
; __device__ __forceinline__ void xcd_barrier(const XcdBarrier& b) {
;     ...
;         const unsigned old = xb_add(&bar[XB_XSUB(b.x)], 1u);
;         const unsigned gen = old / nloc;
;         if (old + 1u == (gen + 1u) * nloc) {
;             __builtin_amdgcn_fence(__ATOMIC_RELEASE, "agent");
;             asm volatile("s_waitcnt vmcnt(0)" ::: "memory");
;             const unsigned og = xb_add(&bar[XB_TOP], 1u);
;             const unsigned tg = og / nx;
;             if (og + 1u == (tg + 1u) * nx) xb_add(&bar[XB_TOPGEN], 1u);
.LBB0_1420:
	s_andn2_saveexec_b64 s[4:5], s[10:11]
	s_cbranch_execz .LBB0_1440
	s_mov_b64 s[10:11], exec
	v_readlane_b32 s3, v255, 40
	s_waitcnt lgkmcnt(0)
	s_cmp_eq_u32 s3, 0
	s_cbranch_scc1 .Lxloc_9
	buffer_wbl2 sc1
	s_waitcnt lgkmcnt(0)
	s_waitcnt vmcnt(0)
	v_mbcnt_lo_u32_b32 v1, s10, 0
	v_mbcnt_hi_u32_b32 v1, s11, v1
	v_cmp_eq_u32_e32 vcc, 0, v1
	s_and_saveexec_b64 s[12:13], vcc
	s_cbranch_execz .LBB0_1423
	s_bcnt1_i32_b64 s3, s[10:11]
	v_mov_b32_e32 v2, 0x3000
	v_mov_b32_e32 v3, s3
	global_atomic_add v2, v2, v3, s[58:59] offset:1024 sc0

; __device__ __forceinline__ unsigned xb_ld(unsigned* p)              { return __hip_atomic_load(p, __ATOMIC_RELAXED, __HIP_MEMORY_SCOPE_AGENT); }
; __device__ __forceinline__ unsigned xb_add(unsigned* p, unsigned v) { return __hip_atomic_fetch_add(p, v, __ATOMIC_RELAXED, __HIP_MEMORY_SCOPE_AGENT); }
; #define XB_SPIN(cond, bar) do { unsigned _sp = 0; while (cond) { __builtin_amdgcn_s_sleep(1); \
;     if ((++_sp & 255u) == 0u) { if (xb_ld(&(bar)[XB_TMO])) break; if (_sp > XB_SPIN_CAP) { atomicAdd(&(bar)[XB_TMO], 1u); break; } } } } while (0)
; __device__ __forceinline__ void xcd_barrier(const XcdBarrier& b) {
;     ...
;             else XB_SPIN(xb_ld(&bar[XB_TOPGEN]) == tg, bar);
;             __builtin_amdgcn_fence(__ATOMIC_ACQUIRE, "agent");
;             xb_add(&bar[XB_XGEN(b.x)], 1u);
;             asm volatile("s_waitcnt vmcnt(0)" ::: "memory");
.Lxloc_9:
	s_mov_b64 s[10:11], exec
	v_mbcnt_lo_u32_b32 v0, s10, 0
	v_mbcnt_hi_u32_b32 v0, s11, v0
	v_cmp_eq_u32_e32 vcc, 0, v0
	s_waitcnt vmcnt(0)
	buffer_inv sc1
	s_and_saveexec_b64 s[12:13], vcc
	s_cbranch_execz .LBB0_1439
	s_bcnt1_i32_b64 s3, s[10:11]
	v_mov_b32_e32 v0, 0x2000
	v_mov_b32_e32 v1, s3
	global_atomic_add v0, v1, s[8:9] offset:1024

; template <class Epi, bool PAIR>
; __device__ __forceinline__ void small_gemm(LAS unsigned char* lds, const bf16_t* A, int lda, const bf16_t* B, int ldb, int K, int nrg, int nct, size_t row_base, int col_base, const Epi& E, int G, int c) {
;     ...
;     for (int unit = c; unit < nrg * nct; unit += G) {
;         const int rg = unit % nrg, ct = unit / nrg;
;         f32x4 acc[4][4];
; #pragma unroll
;         for (int mi = 0; mi < 4; ++mi)
; #pragma unroll
;             for (int ni = 0; ni < 4; ++ni) acc[mi][ni] = (f32x4){0.f, 0.f, 0.f, 0.f};
;         const bf16_t* ap = A + (size_t)(rg * 64 + fr) * lda + k0 + fq * 8;
;         const bf16_t* bp;
;         if (PAIR) { const int ch0 = 32 * ct; bp = B + (size_t)(DSSM + 256 * (ch0 >> 7) + (ch0 & 127) + fr) * ldb + k0 + fq * 8; }
;         else bp = B + (size_t)(ct * 64 + fr) * ldb + k0 + fq * 8;
.LBB0_1484:
	v_readlane_b32 s0, v254, 61
	v_mov_b32_e32 v0, v202
	v_readlane_b32 s1, v254, 62
	s_and_b64 vcc, exec, s[0:1]
	v_readfirstlane_b32 s0, v0
	s_cbranch_vccnz .LBB0_1489
	v_mov_b32_e32 v1, 0x3b00
	s_mov_b32 s4, 0x40000
.Lsmp_p11:
	global_load_dword v2, v1, s[58:59] sc0 sc1
	s_waitcnt vmcnt(0)
	v_readfirstlane_b32 s5, v2
	s_cmpk_ge_u32 s5, 256
	s_cbranch_scc1 .Lsmg_p11
	s_sleep 1
	s_sub_u32 s4, s4, 1
	s_cmp_lg_u32 s4, 0
	s_cbranch_scc1 .Lsmp_p11
.Lsmg_p11:
	buffer_inv sc1
	v_and_b32_e32 v72, 15, v0
	s_lshl_b32 s1, s0, 3
	s_and_b32 s0, s0, 0xfffffc0
	s_and_b32 s4, s1, 0xfffffe00
	v_or_b32_e32 v1, s0, v72
	v_and_b32_e32 v64, 48, v0
	v_ashrrev_i32_e32 v3, 3, v0
	v_and_b32_e32 v0, 7, v0
	s_movk_i32 s0, 0x110
	s_ashr_i32 s5, s4, 31
	v_lshlrev_b32_e32 v4, 5, v0
	v_lshlrev_b32_e32 v74, 3, v0
	v_mul_lo_u32 v0, v3, s0
	v_add3_u32 v75, 0, v4, v0
	v_mul_lo_u32 v0, v1, s0
	s_lshl_b64 s[0:1], s[4:5], 1
	s_add_u32 s0, s58, s0
	v_add_u32_e32 v2, 0, v64
	v_mov_b32_e32 v65, 0
	s_addc_u32 s1, s59, s1
	v_add_u32_e32 v73, 0x8000, v3
	v_add_u32_e32 v76, 0x11000, v75
	v_add_u32_e32 v77, 0x11010, v75
	v_add_u32_e32 v78, 0x15400, v75
	v_add_u32_e32 v79, 0x15410, v75
	v_add_u32_e32 v80, 0x19800, v75
	v_add_u32_e32 v81, 0x19810, v75
	v_add_u32_e32 v82, 0x1dc00, v75
	v_add_u32_e32 v83, 0x1dc10, v75
	v_lshl_add_u64 v[66:67], s[0:1], 0, v[64:65]
	s_mov_b32 s1, 0x1bc00000
	s_mov_b32 s3, 0x1bc20000
	s_mov_b32 s5, 0x1bc40000
	s_mov_b32 s8, 0x1bc60000
	s_mov_b32 s9, 0x1700000
	s_mov_b32 s10, 0x1720000
	s_mov_b32 s11, 0x1740000
	s_mov_b32 s12, 0x1760000
	v_add_u32_e32 v64, v2, v0
	s_mov_b32 s0, 0x3a800000
	s_mov_b32 s4, 0x3f9837f0
